# P7 row-norm loop: cross-row sum-of-squares reduction via v_permlane16/32_swap instead of two ds_bpermute round trips
# speedup vs baseline: 1.0062x; 1.0032x over previous
.LBB0_826:
	s_or_b64 exec, exec, s[16:17]
	v_ashrrev_i32_e32 v64, 11, v64
	v_mul_i32_i24_e32 v64, 0x1800, v64
	v_readlane_b32 s36, v248, 40
	v_ashrrev_i32_e32 v65, 31, v64
	v_readlane_b32 s50, v248, 54
	v_readlane_b32 s51, v248, 55
	s_waitcnt vmcnt(6)
	v_mov_b32_e32 v110, v20
	v_mov_b32_e32 v111, v8
	v_lshl_add_u64 v[64:65], v[64:65], 2, s[50:51]
	v_lshl_add_u64 v[102:103], v[64:65], 0, s[12:13]
	v_lshl_add_u64 v[104:105], v[64:65], 0, s[14:15]
	v_lshl_add_u64 v[64:65], v[102:103], 0, v[48:49]
	v_lshl_add_u64 v[68:69], v[102:103], 0, v[54:55]
	global_load_dwordx4 v[64:67], v[64:65], off
	v_lshl_add_u64 v[86:87], v[104:105], 0, v[48:49]
	global_load_dwordx4 v[68:71], v[68:69], off
	v_lshl_add_u64 v[90:91], v[104:105], 0, v[54:55]
	global_load_dwordx4 v[86:89], v[86:87], off
	v_lshl_add_u64 v[94:95], v[102:103], 0, v[56:57]
	global_load_dwordx4 v[90:93], v[90:91], off
	v_lshl_add_u64 v[98:99], v[104:105], 0, v[56:57]
	global_load_dwordx4 v[94:97], v[94:95], off
	s_nop 0
	global_load_dwordx4 v[98:101], v[98:99], off
	v_lshl_add_u64 v[102:103], v[102:103], 0, v[58:59]
	v_lshl_add_u64 v[106:107], v[104:105], 0, v[58:59]
	global_load_dwordx4 v[102:105], v[102:103], off
	s_nop 0
	global_load_dwordx4 v[106:109], v[106:107], off
	v_mov_b32_e32 v112, v21
	v_mov_b32_e32 v113, v9
	s_waitcnt vmcnt(10)
	v_mov_b32_e32 v118, v28
	v_mov_b32_e32 v119, v24
	v_pk_mul_f32 v[110:111], v[110:111], v[110:111]
	v_mov_b32_e32 v114, v22
	v_mov_b32_e32 v115, v10
	v_mov_b32_e32 v120, v29
	v_mov_b32_e32 v121, v25
	v_pk_mul_f32 v[118:119], v[118:119], v[118:119]
	v_pk_fma_f32 v[110:111], v[112:113], v[112:113], v[110:111]
	v_mov_b32_e32 v116, v23
	v_mov_b32_e32 v117, v11
	v_mov_b32_e32 v122, v30
	v_mov_b32_e32 v123, v26
	v_pk_fma_f32 v[112:113], v[120:121], v[120:121], v[118:119]
	v_pk_fma_f32 v[110:111], v[114:115], v[114:115], v[110:111]
	v_mov_b32_e32 v124, v31
	v_mov_b32_e32 v125, v27
	v_pk_fma_f32 v[112:113], v[122:123], v[122:123], v[112:113]
	v_pk_fma_f32 v[110:111], v[116:117], v[116:117], v[110:111]
	v_pk_fma_f32 v[112:113], v[124:125], v[124:125], v[112:113]
	v_add_f32_e32 v110, v110, v111
	v_add_f32_e32 v110, v113, v110
	v_add_f32_e32 v110, v112, v110
	s_and_b64 s[16:17], exec, vcc
	s_or_b64 s[10:11], s[16:17], s[10:11]
	v_add_f32_dpp v110, v110, v110 row_ror:8 row_mask:0xf bank_mask:0xf bound_ctrl:1
	v_lshl_add_u64 v[50:51], v[50:51], 0, s[4:5]
	v_readlane_b32 s37, v248, 41
	v_add_f32_dpp v110, v110, v110 row_ror:4 row_mask:0xf bank_mask:0xf bound_ctrl:1
	v_readlane_b32 s38, v248, 42
	v_readlane_b32 s39, v248, 43
	v_add_f32_dpp v110, v110, v110 row_ror:2 row_mask:0xf bank_mask:0xf bound_ctrl:1
	v_readlane_b32 s40, v248, 44
	v_readlane_b32 s41, v248, 45
	v_add_f32_dpp v110, v110, v110 row_ror:1 row_mask:0xf bank_mask:0xf bound_ctrl:1
	s_nop 1
	v_mov_b32_e32 v111, v110
	s_nop 1
	v_permlane16_swap_b32_e32 v111, v110
	s_nop 1
	v_readlane_b32 s42, v248, 46
	v_readlane_b32 s43, v248, 47
	v_readlane_b32 s44, v248, 48
	v_readlane_b32 s45, v248, 49
	s_waitcnt lgkmcnt(0)
	v_add_f32_e32 v110, v110, v111
	s_nop 1
	v_mov_b32_e32 v111, v110
	s_nop 1
	v_permlane32_swap_b32_e32 v111, v110
	s_nop 1
	v_readlane_b32 s46, v248, 50
	v_readlane_b32 s47, v248, 51
	v_readlane_b32 s48, v248, 52
	v_readlane_b32 s49, v248, 53
	s_waitcnt lgkmcnt(0)
	v_add_f32_e32 v110, v110, v111
	v_fmamk_f32 v110, v110, 0x3a800000, v62
	v_mul_f32_e32 v111, 0x4b800000, v110
	v_cmp_gt_f32_e64 s[0:1], s20, v110
	s_waitcnt vmcnt(7)
	v_pk_add_f32 v[64:65], v[64:65], 1.0 op_sel_hi:[1,0]
	v_cndmask_b32_e64 v110, v110, v111, s[0:1]
	v_rsq_f32_e32 v110, v110
	v_pk_add_f32 v[66:67], v[66:67], 1.0 op_sel_hi:[1,0]
	s_waitcnt vmcnt(6)
	v_pk_add_f32 v[68:69], v[68:69], 1.0 op_sel_hi:[1,0]
	v_pk_add_f32 v[70:71], v[70:71], 1.0 op_sel_hi:[1,0]
	v_mul_f32_e32 v111, 0x45800000, v110
	v_cndmask_b32_e64 v110, v110, v111, s[0:1]
	v_pk_mul_f32 v[8:9], v[8:9], v[110:111] op_sel_hi:[1,0]
	v_pk_mul_f32 v[10:11], v[10:11], v[110:111] op_sel_hi:[1,0]
	v_pk_mul_f32 v[20:21], v[20:21], v[110:111] op_sel_hi:[1,0]
	v_pk_mul_f32 v[22:23], v[22:23], v[110:111] op_sel_hi:[1,0]
	v_pk_mul_f32 v[8:9], v[0:1], v[8:9]
	v_pk_mul_f32 v[10:11], v[2:3], v[10:11]
	v_pk_mul_f32 v[20:21], v[4:5], v[20:21]
	v_pk_mul_f32 v[22:23], v[6:7], v[22:23]
	s_waitcnt vmcnt(5)
	v_pk_fma_f32 v[8:9], v[64:65], v[8:9], v[86:87]
	v_pk_fma_f32 v[10:11], v[66:67], v[10:11], v[88:89]
	s_waitcnt vmcnt(4)
	v_pk_fma_f32 v[20:21], v[20:21], v[68:69], v[90:91]
	v_pk_fma_f32 v[22:23], v[22:23], v[70:71], v[92:93]
	v_cvt_pk_bf16_f32 v8, v8, v9
	v_cvt_pk_bf16_f32 v9, v10, v11
	v_cvt_pk_bf16_f32 v10, v20, v21
	v_cvt_pk_bf16_f32 v11, v22, v23
	v_pk_mul_f32 v[24:25], v[24:25], v[110:111] op_sel_hi:[1,0]
	global_store_dwordx2 v[52:53], v[8:9], off
	global_store_dwordx2 v[52:53], v[10:11], off offset:512
	v_pk_mul_f32 v[10:11], v[26:27], v[110:111] op_sel_hi:[1,0]
	v_pk_mul_f32 v[24:25], v[12:13], v[24:25]
	s_waitcnt vmcnt(5)
	v_pk_add_f32 v[8:9], v[94:95], 1.0 op_sel_hi:[1,0]
	v_pk_mul_f32 v[10:11], v[14:15], v[10:11]
	v_pk_add_f32 v[20:21], v[96:97], 1.0 op_sel_hi:[1,0]
	s_waitcnt vmcnt(4)
	v_pk_fma_f32 v[8:9], v[24:25], v[8:9], v[98:99]
	v_pk_fma_f32 v[10:11], v[10:11], v[20:21], v[100:101]
	v_cvt_pk_bf16_f32 v8, v8, v9
	v_cvt_pk_bf16_f32 v9, v10, v11
	global_store_dwordx2 v[52:53], v[8:9], off offset:1024
	v_pk_mul_f32 v[8:9], v[28:29], v[110:111] op_sel_hi:[1,0]
	s_waitcnt vmcnt(4)
	v_pk_add_f32 v[10:11], v[102:103], 1.0 op_sel_hi:[1,0]
	v_pk_mul_f32 v[8:9], v[16:17], v[8:9]
	v_pk_add_f32 v[20:21], v[104:105], 1.0 op_sel_hi:[1,0]
	s_waitcnt vmcnt(3)
	v_pk_fma_f32 v[8:9], v[8:9], v[10:11], v[106:107]
	v_pk_mul_f32 v[10:11], v[30:31], v[110:111] op_sel_hi:[1,0]
	v_cvt_pk_bf16_f32 v8, v8, v9
	v_pk_mul_f32 v[10:11], v[18:19], v[10:11]
	v_mov_b32_e32 v64, v63
	v_pk_fma_f32 v[10:11], v[10:11], v[20:21], v[108:109]
	v_mov_b64_e32 v[22:23], v[38:39]
	v_cvt_pk_bf16_f32 v9, v10, v11
	global_store_dwordx2 v[52:53], v[8:9], off offset:1536
	v_lshl_add_u64 v[52:53], v[52:53], 0, s[8:9]
	v_mov_b64_e32 v[10:11], v[34:35]
	v_mov_b64_e32 v[8:9], v[32:33]
	v_mov_b64_e32 v[20:21], v[36:37]
	v_mov_b64_e32 v[26:27], v[42:43]
	v_mov_b64_e32 v[24:25], v[40:41]
	v_mov_b64_e32 v[30:31], v[46:47]
	v_mov_b64_e32 v[28:29], v[44:45]
	s_andn2_b64 exec, exec, s[10:11]
	s_cbranch_execz .LBB0_829
